# diff loop row sums accumulated with packed f32 adds (two partial sums), plus small VALU trims and NA scalar-base prefetch
# baseline (speedup 1.0000x reference)
; DI bool softmax_tile(f32x16& s0, f32x16& s1, float& m, float& l, float& alpha, bf16x8* pf, int lane, bool first, bool check) {
;     ...
;   float sum = 0.f;
; #pragma unroll
;   for (int i = 0; i < 16; ++i) { s0[i] = __builtin_amdgcn_exp2f(s0[i]); sum += s0[i]; }
; #pragma unroll
;   for (int i = 0; i < 16; ++i) { s1[i] = __builtin_amdgcn_exp2f(s1[i]); sum += s1[i]; }
;   l += sum;
;   pf[0] = pack8(s0, 0); pf[1] = pack8(s0, 8); pf[2] = pack8(s1, 0); pf[3] = pack8(s1, 8);
;   alpha = 1.f;
;   if (!check) return false;
;   const float rsum = sum + shx(sum, 32, lane);
;   const bool trig = rsum > 65536.f;
;   const bool resc = (__builtin_amdgcn_ballot_w64(trig) != 0ull);
;   alpha = 1.f;
;   if (resc) {
;     const float d = trig ? (float)(__builtin_amdgcn_frexp_expf(rsum) - 7) : 0.f;
;     alpha = __builtin_amdgcn_exp2f(-d);
;     m += d; l *= alpha;
;   }
.LBB0_572:
	v_add3_u32 v175, s45, v164, v163
	ds_read_b128 v[212:215], v174 offset:17408
	ds_read_b128 v[216:219], v174 offset:26112
	ds_read_b128 v[220:223], v174 offset:17440
	ds_read_b128 v[224:227], v174 offset:26144
	ds_read_b128 v[228:231], v174 offset:17472
	ds_read_b128 v[232:235], v174 offset:26176
	ds_read_b128 v[176:179], v174 offset:17504
	ds_read_b128 v[242:245], v174 offset:26208
	v_add_u32_e32 v236, 0x8800, v175
	v_exp_f32_e32 v80, v80
	v_exp_f32_e32 v81, v81
	v_exp_f32_e32 v82, v82
	v_exp_f32_e32 v83, v83
	v_exp_f32_e32 v84, v84
	v_exp_f32_e32 v85, v85
	v_pk_add_f32 v[254:255], v[80:81], v[82:83]
	v_exp_f32_e32 v86, v86
	v_exp_f32_e32 v87, v87
	v_pk_add_f32 v[254:255], v[254:255], v[84:85]
	v_exp_f32_e32 v88, v88
	v_exp_f32_e32 v89, v89
	v_pk_add_f32 v[254:255], v[254:255], v[86:87]
	v_exp_f32_e32 v90, v90
	v_exp_f32_e32 v91, v91
	v_pk_add_f32 v[254:255], v[254:255], v[88:89]
	v_exp_f32_e32 v92, v92
	v_exp_f32_e32 v93, v93
	v_pk_add_f32 v[254:255], v[254:255], v[90:91]
	v_exp_f32_e32 v94, v94
	v_exp_f32_e32 v95, v95
	v_pk_add_f32 v[254:255], v[254:255], v[92:93]
	v_exp_f32_e32 v64, v64
	v_exp_f32_e32 v65, v65
	v_pk_add_f32 v[254:255], v[254:255], v[94:95]
	v_exp_f32_e32 v66, v66
	v_exp_f32_e32 v67, v67
	v_pk_add_f32 v[254:255], v[254:255], v[64:65]
	v_exp_f32_e32 v68, v68
	v_exp_f32_e32 v69, v69
	v_pk_add_f32 v[254:255], v[254:255], v[66:67]
	v_exp_f32_e32 v70, v70
	v_exp_f32_e32 v71, v71
	v_pk_add_f32 v[254:255], v[254:255], v[68:69]
	v_exp_f32_e32 v72, v72
	v_exp_f32_e32 v73, v73
	v_pk_add_f32 v[254:255], v[254:255], v[70:71]
	v_exp_f32_e32 v74, v74
	v_exp_f32_e32 v75, v75
	v_pk_add_f32 v[254:255], v[254:255], v[72:73]
	v_exp_f32_e32 v76, v76
	v_exp_f32_e32 v77, v77
	v_pk_add_f32 v[254:255], v[254:255], v[74:75]
	v_exp_f32_e32 v78, v78
	v_exp_f32_e32 v79, v79
	v_pk_add_f32 v[254:255], v[254:255], v[76:77]
	v_pk_add_f32 v[254:255], v[254:255], v[78:79]
	v_add_f32_e32 v250, v254, v255
	s_and_b32 s2, s43, 3
	v_add_f32_e32 v172, v172, v250
	s_mov_b64 s[100:101], 0
	s_cmp_lg_u32 s2, 0
	s_cbranch_scc1 .Ldp_ck_done
	ds_bpermute_b32 v251, v147, v250
	s_waitcnt lgkmcnt(0)
	v_add_f32_e32 v250, v250, v251
	v_cmp_lt_f32_e32 vcc, s88, v250
	s_cbranch_vccz .Ldp_ck_done
	v_frexp_exp_i32_f32_e32 v251, v250
	v_add_u32_e32 v251, -7, v251
	v_cvt_f32_i32_e32 v251, v251
	s_mov_b64 s[100:101], -1
	v_cndmask_b32_e32 v251, 0, v251, vcc
	v_exp_f32_e64 v252, -v251
	v_add_f32_e32 v169, v169, v251
	v_mul_f32_e32 v172, v172, v252

; DI f32x16 mfma32(bf16x8 a, bf16x8 b, f32x16 c) { return __builtin_amdgcn_mfma_f32_32x32x16_bf16(a, b, c, 0, 0, 0); }
; DI bool softmax_tile(f32x16& s0, f32x16& s1, float& m, float& l, float& alpha, bf16x8* pf, int lane, bool first, bool check) {
;     ...
;   float sum = 0.f;
; #pragma unroll
;   for (int i = 0; i < 16; ++i) { s0[i] = __builtin_amdgcn_exp2f(s0[i]); sum += s0[i]; }
; #pragma unroll
;   for (int i = 0; i < 16; ++i) { s1[i] = __builtin_amdgcn_exp2f(s1[i]); sum += s1[i]; }
;   l += sum;
;   pf[0] = pack8(s0, 0); pf[1] = pack8(s0, 8); pf[2] = pack8(s1, 0); pf[3] = pack8(s1, 8);
; DI void attn_diff_unit(const Params& p, int li, int b, int h, int qb, char* smem, bool pre, int nh, bool has_next) {
;     ...
;       {
;         bf16x8 vf[2][4];
; #pragma unroll
;         for (int j = 0; j < 4; ++j) vf[0][j] = ld_vfrag_tr(vs, vbase, VR, sub * 64, j * 32);
; #pragma unroll
;         for (int s = 0; s < 4; ++s) {
;           if (s < 3) {
; #pragma unroll
;             for (int j = 0; j < 4; ++j) vf[(s + 1) & 1][j] = ld_vfrag_tr(vs, vbase, VR, sub * 64 + 16 * (s + 1), j * 32);
;           }
;           __builtin_amdgcn_sched_barrier(0); __builtin_amdgcn_s_setprio(1);
; #pragma unroll
;           for (int j = 0; j < 4; ++j) O[j] = mfma32(vf[s & 1][j], pf[s], O[j]);
;         __builtin_amdgcn_s_setprio(0);
; }
;       }
;       if (resc) {
; #pragma unroll
;         for (int j = 0; j < 4; ++j) scale16(O[j], alpha);
;       }
.Ldp_b1_skip:
	ds_read_b64_tr_b16 v[212:213], v175 offset:34816
	ds_read_b64_tr_b16 v[214:215], v175 offset:37376
	ds_read_b64_tr_b16 v[216:217], v175 offset:34880
	ds_read_b64_tr_b16 v[218:219], v175 offset:37440
	ds_read_b64_tr_b16 v[220:221], v175 offset:34944
	ds_read_b64_tr_b16 v[222:223], v175 offset:37504
	ds_read_b64_tr_b16 v[224:225], v175 offset:35008
	ds_read_b64_tr_b16 v[226:227], v175 offset:37568
	ds_read_b64_tr_b16 v[228:229], v175 offset:39936
	ds_read_b64_tr_b16 v[230:231], v175 offset:42496
	ds_read_b64_tr_b16 v[232:233], v175 offset:40000
	ds_read_b64_tr_b16 v[234:235], v175 offset:42560
	ds_read_b64_tr_b16 v[176:177], v175 offset:40064
	ds_read_b64_tr_b16 v[178:179], v175 offset:42624
	ds_read_b64_tr_b16 v[242:243], v175 offset:40128
	ds_read_b64_tr_b16 v[244:245], v175 offset:42688
	s_waitcnt lgkmcnt(8)
	v_mfma_f32_32x32x16_bf16 v[48:63], v[212:215], v[72:75], v[48:63]
	v_exp_f32_e32 v80, v80
	v_exp_f32_e32 v81, v81
	v_mfma_f32_32x32x16_bf16 v[32:47], v[216:219], v[72:75], v[32:47]
	v_exp_f32_e32 v82, v82
	v_exp_f32_e32 v83, v83
	v_mfma_f32_32x32x16_bf16 v[16:31], v[220:223], v[72:75], v[16:31]
	v_exp_f32_e32 v84, v84
	v_exp_f32_e32 v85, v85
	v_pk_add_f32 v[254:255], v[80:81], v[82:83]
	v_mfma_f32_32x32x16_bf16 v[0:15], v[224:227], v[72:75], v[0:15]
	v_exp_f32_e32 v86, v86
	v_exp_f32_e32 v87, v87
	v_pk_add_f32 v[254:255], v[254:255], v[84:85]
	ds_read_b64_tr_b16 v[212:213], v175 offset:45056
	ds_read_b64_tr_b16 v[214:215], v175 offset:47616
	ds_read_b64_tr_b16 v[216:217], v175 offset:45120
	ds_read_b64_tr_b16 v[218:219], v175 offset:47680
	ds_read_b64_tr_b16 v[220:221], v175 offset:45184
	ds_read_b64_tr_b16 v[222:223], v175 offset:47744
	ds_read_b64_tr_b16 v[224:225], v175 offset:45248
	ds_read_b64_tr_b16 v[226:227], v175 offset:47808
	s_waitcnt lgkmcnt(8)
	v_mfma_f32_32x32x16_bf16 v[48:63], v[228:231], v[76:79], v[48:63]
	v_exp_f32_e32 v88, v88
	v_exp_f32_e32 v89, v89
	v_pk_add_f32 v[254:255], v[254:255], v[86:87]
	v_cvt_pk_bf16_f32 v80, v80, v81
	v_mfma_f32_32x32x16_bf16 v[32:47], v[232:235], v[76:79], v[32:47]
	v_exp_f32_e32 v90, v90
	v_exp_f32_e32 v91, v91
	v_pk_add_f32 v[254:255], v[254:255], v[88:89]
	v_cvt_pk_bf16_f32 v81, v82, v83
	v_mfma_f32_32x32x16_bf16 v[16:31], v[176:179], v[76:79], v[16:31]
	v_exp_f32_e32 v92, v92
	v_exp_f32_e32 v93, v93
	v_pk_add_f32 v[254:255], v[254:255], v[90:91]
	v_cvt_pk_bf16_f32 v82, v84, v85
	v_mfma_f32_32x32x16_bf16 v[0:15], v[242:245], v[76:79], v[0:15]
	v_exp_f32_e32 v94, v94
	v_exp_f32_e32 v95, v95
	v_pk_add_f32 v[254:255], v[254:255], v[92:93]
	v_cvt_pk_bf16_f32 v83, v86, v87
	ds_read_b64_tr_b16 v[228:229], v175 offset:50176
	ds_read_b64_tr_b16 v[230:231], v175 offset:52736
	ds_read_b64_tr_b16 v[232:233], v175 offset:50240
	ds_read_b64_tr_b16 v[234:235], v175 offset:52800
	ds_read_b64_tr_b16 v[176:177], v175 offset:50304
	ds_read_b64_tr_b16 v[178:179], v175 offset:52864
	ds_read_b64_tr_b16 v[242:243], v175 offset:50368
	ds_read_b64_tr_b16 v[244:245], v175 offset:52928
	s_waitcnt lgkmcnt(8)
	v_mfma_f32_32x32x16_bf16 v[48:63], v[212:215], v[64:67], v[48:63]
	v_exp_f32_e32 v196, v196
	v_exp_f32_e32 v197, v197
	v_pk_add_f32 v[254:255], v[254:255], v[94:95]
	v_cvt_pk_bf16_f32 v84, v88, v89
	v_mfma_f32_32x32x16_bf16 v[32:47], v[216:219], v[64:67], v[32:47]
	v_exp_f32_e32 v198, v198
	v_exp_f32_e32 v199, v199
	v_pk_add_f32 v[254:255], v[254:255], v[196:197]
	v_cvt_pk_bf16_f32 v85, v90, v91
	v_mfma_f32_32x32x16_bf16 v[16:31], v[220:223], v[64:67], v[16:31]
	v_exp_f32_e32 v200, v200
	v_exp_f32_e32 v201, v201
	v_pk_add_f32 v[254:255], v[254:255], v[198:199]
	v_cvt_pk_bf16_f32 v86, v92, v93
	v_mfma_f32_32x32x16_bf16 v[0:15], v[224:227], v[64:67], v[0:15]
	v_exp_f32_e32 v202, v202
	v_exp_f32_e32 v203, v203
	v_pk_add_f32 v[254:255], v[254:255], v[200:201]
	v_cvt_pk_bf16_f32 v87, v94, v95
	s_waitcnt lgkmcnt(0)
	v_mfma_f32_32x32x16_bf16 v[48:63], v[228:231], v[68:71], v[48:63]
	v_exp_f32_e32 v204, v204
	v_exp_f32_e32 v205, v205
	v_pk_add_f32 v[254:255], v[254:255], v[202:203]
	v_cvt_pk_bf16_f32 v196, v196, v197
	v_mfma_f32_32x32x16_bf16 v[32:47], v[232:235], v[68:71], v[32:47]
	v_exp_f32_e32 v206, v206
	v_exp_f32_e32 v207, v207
	v_pk_add_f32 v[254:255], v[254:255], v[204:205]
	v_cvt_pk_bf16_f32 v197, v198, v199
	v_mfma_f32_32x32x16_bf16 v[16:31], v[176:179], v[68:71], v[16:31]
	v_exp_f32_e32 v208, v208
	v_exp_f32_e32 v209, v209
	v_pk_add_f32 v[254:255], v[254:255], v[206:207]
	v_cvt_pk_bf16_f32 v198, v200, v201
	v_mfma_f32_32x32x16_bf16 v[0:15], v[242:245], v[68:71], v[0:15]
	v_exp_f32_e32 v210, v210
	v_exp_f32_e32 v211, v211
	v_pk_add_f32 v[254:255], v[254:255], v[208:209]
	v_cvt_pk_bf16_f32 v199, v202, v203
	v_pk_add_f32 v[254:255], v[254:255], v[210:211]
	v_cvt_pk_bf16_f32 v200, v204, v205
	v_cvt_pk_bf16_f32 v201, v206, v207
	v_cvt_pk_bf16_f32 v202, v208, v209
	v_cvt_pk_bf16_f32 v203, v210, v211
	v_add_f32_e32 v253, v254, v255
	v_add_f32_e32 v172, v172, v253
	s_andn2_b64 vcc, exec, s[100:101]
	s_cbranch_vccnz .Ldp_nors
	s_nop 15
	v_mul_f32_e32 v0, v0, v252
	v_mul_f32_e32 v1, v1, v252
	v_mul_f32_e32 v2, v2, v252
	v_mul_f32_e32 v3, v3, v252
	v_mul_f32_e32 v4, v4, v252
	v_mul_f32_e32 v5, v5, v252
	v_mul_f32_e32 v6, v6, v252
	v_mul_f32_e32 v7, v7, v252
	v_mul_f32_e32 v8, v8, v252
	v_mul_f32_e32 v9, v9, v252
	v_mul_f32_e32 v10, v10, v252
	v_mul_f32_e32 v11, v11, v252
	v_mul_f32_e32 v12, v12, v252
	v_mul_f32_e32 v13, v13, v252
	v_mul_f32_e32 v14, v14, v252
	v_mul_f32_e32 v15, v15, v252
	v_mul_f32_e32 v16, v16, v252
	v_mul_f32_e32 v17, v17, v252
	v_mul_f32_e32 v18, v18, v252
	v_mul_f32_e32 v19, v19, v252
	v_mul_f32_e32 v20, v20, v252
	v_mul_f32_e32 v21, v21, v252
	v_mul_f32_e32 v22, v22, v252
	v_mul_f32_e32 v23, v23, v252
	v_mul_f32_e32 v24, v24, v252
	v_mul_f32_e32 v25, v25, v252
	v_mul_f32_e32 v26, v26, v252
	v_mul_f32_e32 v27, v27, v252
	v_mul_f32_e32 v28, v28, v252
	v_mul_f32_e32 v29, v29, v252
	v_mul_f32_e32 v30, v30, v252
	v_mul_f32_e32 v31, v31, v252
	v_mul_f32_e32 v32, v32, v252
	v_mul_f32_e32 v33, v33, v252
	v_mul_f32_e32 v34, v34, v252
	v_mul_f32_e32 v35, v35, v252
	v_mul_f32_e32 v36, v36, v252
	v_mul_f32_e32 v37, v37, v252
	v_mul_f32_e32 v38, v38, v252
	v_mul_f32_e32 v39, v39, v252
	v_mul_f32_e32 v40, v40, v252
	v_mul_f32_e32 v41, v41, v252
	v_mul_f32_e32 v42, v42, v252
	v_mul_f32_e32 v43, v43, v252
	v_mul_f32_e32 v44, v44, v252
	v_mul_f32_e32 v45, v45, v252
	v_mul_f32_e32 v46, v46, v252
	v_mul_f32_e32 v47, v47, v252
	v_mul_f32_e32 v48, v48, v252
	v_mul_f32_e32 v49, v49, v252
	v_mul_f32_e32 v50, v50, v252
	v_mul_f32_e32 v51, v51, v252
	v_mul_f32_e32 v52, v52, v252
	v_mul_f32_e32 v53, v53, v252
	v_mul_f32_e32 v54, v54, v252
	v_mul_f32_e32 v55, v55, v252
	v_mul_f32_e32 v56, v56, v252
	v_mul_f32_e32 v57, v57, v252
	v_mul_f32_e32 v58, v58, v252
	v_mul_f32_e32 v59, v59, v252
	v_mul_f32_e32 v60, v60, v252
	v_mul_f32_e32 v61, v61, v252
	v_mul_f32_e32 v62, v62, v252
	v_mul_f32_e32 v63, v63, v252
